# latent attention unit prologue: second key tile's K/V loads issued together with the first tile's (counted waits adjusted) instead of after the first LDS fill and barrier
# baseline (speedup 1.0000x reference)
; __device__ __forceinline__ int fresh_tid() { int t = threadIdx.x; asm volatile("" : "+v"(t)); return t; }
; #define ATT_LOAD(set, t) do { rk1[set] = *(const u32x4*)(k1src + (size_t)(t) * 64 * 256); rk2[set] = *(const u32x4*)(k2src + (size_t)(t) * 64 * 256); \
;         rv0[set] = *(const u32x4*)(vsrc + (t) * 64); rv1[set] = *(const u32x4*)(vsrc + (size_t)64 * KCAT + (t) * 64); } while (0)
; __device__ __forceinline__ void attn_unit(LAS unsigned char* lds, const Args& A, int b, int h, int qrow0, int nkt) {
;     const int tid = fresh_tid(), lane = tid & 63, r32 = lane & 31, hi = lane >> 5;
;     const int wid = __builtin_amdgcn_readfirstlane(tid >> 6), map = wid >> 2, qg = wid & 3;
;     const bf16_t* Qm = map ? A.Q2 : A.Q1;
;     bf16x8 qf[4];
;     { const bf16_t* qp = Qm + (size_t)(qrow0 + qg * 32 + r32) * 256 + h * 64 + hi * 8;
; #pragma unroll
;       for (int d0 = 0; d0 < 4; ++d0) qf[d0] = *(const bf16x8*)(qp + d0 * 16); }
;     const int key_s = tid >> 3, ch_s = tid & 7;
;     const bf16_t* k1src = A.K1c + ((size_t)b * KCAT + key_s) * 256 + h * 64 + ch_s * 8;
;     const bf16_t* k2src = A.K2c + ((size_t)b * KCAT + key_s) * 256 + h * 64 + ch_s * 8;
;     const bf16_t* vsrc = A.VT + ((size_t)(b * 4 + h) * 128 + key_s) * KCAT + ch_s * 8;
;     const int kdst = key_s * 128 + ((ch_s ^ ((key_s >> 1) & 7)) << 4), vdst = key_s * VP + 32 * (ch_s >> 1) + 8 * (ch_s & 1);
;     u32x4 rk1[2], rk2[2], rv0[2], rv1[2];
;     ...
;     constexpr float THR = 6.f;
;     float mrun = 0.f, lrun = 0.f;
;     f32x16 O[4];
; #pragma unroll
;     for (int i = 0; i < 4; ++i)
; #pragma unroll
;         for (int r = 0; r < 16; ++r) O[i][r] = 0.f;
;     ATT_LOAD(0, 0); ATT_STORE(0, 0); __syncthreads();
;     ATT_LOAD(1, 1);
.LBB0_691:
	s_and_b64 vcc, exec, s[0:1]
	s_cbranch_vccz .LBB0_672
	s_ashr_i32 s8, s11, 6
	s_lshl_b32 s1, s11, 7
	v_mov_b32_e32 v10, v192
	s_lshl_b32 s0, s8, 11
	s_and_b32 s1, s1, 0x780
	s_bfe_u32 s12, s11, 0x20004
	v_readfirstlane_b32 s13, v10
	s_or_b32 s9, s0, s1
	s_bfe_u32 s14, s13, 0x20006
	s_cmpk_lt_u32 s13, 0x100
	s_cselect_b64 s[0:1], -1, 0
	s_and_b64 s[6:7], s[0:1], exec
	v_readlane_b32 s6, v253, 10
	v_readlane_b32 s7, v253, 11
	s_cselect_b32 s7, s23, s7
	s_cselect_b32 s6, s22, s6
	s_lshl_b32 s15, s14, 5
	v_and_b32_e32 v11, 31, v10
	s_or_b32 s9, s15, s9
	v_or_b32_e32 v172, s9, v11
	v_ashrrev_i32_e32 v173, 31, v172
	v_lshlrev_b64 v[0:1], 9, v[172:173]
	v_bfe_u32 v184, v10, 5, 1
	v_lshl_add_u64 v[0:1], s[6:7], 0, v[0:1]
	s_lshl_b32 s42, s12, 7
	v_lshl_add_u64 v[0:1], v[0:1], 0, s[42:43]
	v_lshlrev_b32_e32 v170, 4, v184
	v_mov_b32_e32 v171, v161
	v_lshl_add_u64 v[0:1], v[0:1], 0, v[170:171]
	global_load_dwordx4 v[96:99], v[0:1], off
	global_load_dwordx4 v[100:103], v[0:1], off offset:32
	global_load_dwordx4 v[104:107], v[0:1], off offset:64
	global_load_dwordx4 v[108:111], v[0:1], off offset:96
	v_ashrrev_i32_e32 v0, 3, v10
	v_ashrrev_i32_e32 v1, 31, v0
	v_mad_i64_i32 v[2:3], s[6:7], s8, v206, v[0:1]
	v_readlane_b32 s6, v253, 8
	v_lshlrev_b64 v[2:3], 9, v[2:3]
	v_readlane_b32 s7, v253, 9
	s_movk_i32 s30, 0x1200
	s_movk_i32 s9, 0x90
	v_lshl_add_u64 v[4:5], s[6:7], 0, v[2:3]
	v_readlane_b32 s6, v253, 5
	v_readlane_b32 s7, v253, 6
	v_lshlrev_b32_e32 v13, 3, v10
	v_lshl_add_u64 v[4:5], v[4:5], 0, s[42:43]
	v_lshl_add_u64 v[2:3], s[6:7], 0, v[2:3]
	s_lshl_b32 s6, s8, 2
	s_or_b32 s6, s6, s12
	s_ashr_i32 s7, s6, 31
	s_lshl_b64 s[24:25], s[6:7], 7
	v_lshl_add_u64 v[6:7], s[24:25], 0, v[0:1]
	v_readlane_b32 s24, v253, 1
	v_readlane_b32 s25, v253, 2
	s_movk_i32 s7, 0x70
	v_lshl_add_u64 v[2:3], v[2:3], 0, s[42:43]
	v_mov_b64_e32 v[8:9], s[24:25]
	v_mad_u64_u32 v[8:9], s[24:25], v6, s30, v[8:9]
	v_mad_i32_i24 v9, v7, s30, v9
	v_lshlrev_b32_e32 v7, 4, v10
	v_lshlrev_b32_e32 v6, 7, v0
	v_xor_b32_e32 v12, v7, v10
	v_and_or_b32 v12, v12, s7, v6
	v_and_b32_e32 v160, 0x70, v7
	v_and_b32_e32 v6, 0x60, v7
	v_lshl_add_u64 v[8:9], v[8:9], 0, v[160:161]
	v_mad_u64_u32 v[6:7], s[24:25], v0, s9, v[6:7]
	s_mov_b32 s7, 0x48000
	v_and_or_b32 v13, v13, 8, v6
	v_add_co_u32_e32 v6, vcc, s7, v8
	v_lshl_add_u64 v[4:5], v[4:5], 0, v[160:161]
	s_nop 0
	v_addc_co_u32_e32 v7, vcc, 0, v9, vcc
	v_lshl_add_u64 v[2:3], v[2:3], 0, v[160:161]
	global_load_dwordx4 v[112:115], v[4:5], off
	global_load_dwordx4 v[116:119], v[2:3], off
	global_load_dwordx4 v[120:123], v[8:9], off
	global_load_dwordx4 v[124:127], v[6:7], off
	s_mov_b32 s7, 0x8000
	v_add_co_u32_e32 v4, vcc, s7, v4
	v_add_u32_e32 v185, 0, v13
	s_nop 0
	v_addc_co_u32_e32 v5, vcc, 0, v5, vcc
	v_add_co_u32_e32 v2, vcc, s7, v2
	v_add_u32_e32 v171, 0, v12
	v_add_u32_e32 v186, 0x4000, v185
	v_add_u32_e32 v187, 0x6000, v185
	v_addc_co_u32_e32 v3, vcc, 0, v3, vcc
	global_load_dwordx4 v[128:131], v[4:5], off
	global_load_dwordx4 v[132:135], v[2:3], off
	global_load_dwordx4 v[136:139], v[8:9], off offset:128
	global_load_dwordx4 v[140:143], v[6:7], off offset:128
	s_and_b64 s[24:25], s[0:1], exec
	s_cselect_b32 s7, 0, 0x2000
	v_readlane_b32 s52, v252, 0
	s_add_i32 s7, s7, 0
	v_readlane_b32 s56, v252, 4
	v_mad_u32_u24 v21, v11, s9, 0
	v_readlane_b32 s57, v252, 5
	s_add_u32 s9, s56, s42
	v_lshl_add_u32 v16, v11, 7, s7
	s_mul_hi_i32 s7, s8, 0x120000
	s_mul_i32 s8, s8, 0x120000
	s_addc_u32 s20, s57, 0
	s_add_u32 s8, s9, s8
	s_addc_u32 s9, s20, s7
	s_mul_hi_i32 s7, s6, 0x90000
	s_mul_i32 s6, s6, 0x90000
	s_add_u32 s6, s56, s6
	s_addc_u32 s7, s57, s7
	v_mov_b32_e32 v14, v161
	v_mov_b32_e32 v15, v161
	v_and_b32_e32 v166, 63, v10
	v_mov_b32_e32 v11, v161
	s_waitcnt vmcnt(7)
	ds_write_b128 v171, v[112:115]
	s_waitcnt vmcnt(6)
	ds_write_b128 v171, v[116:119] offset:8192
	s_waitcnt vmcnt(5)
	ds_write2_b64 v186, v[120:121], v[122:123] offset1:2
	s_waitcnt vmcnt(4)
	ds_write2_b64 v187, v[124:125], v[126:127] offset0:128 offset1:130
	s_waitcnt lgkmcnt(0)
	s_barrier
	v_lshrrev_b32_e32 v2, 1, v10
	v_bfe_u32 v3, v10, 1, 3
	v_bitop3_b32 v2, v184, v2, 7 bitop3:0x78
	v_lshlrev_b32_e32 v17, 4, v2
	v_bitop3_b32 v2, v184, v3, 2 bitop3:0x36
	v_lshlrev_b32_e32 v18, 4, v2
	v_bitop3_b32 v2, v184, v3, 4 bitop3:0x36
	v_lshlrev_b32_e32 v19, 4, v2
	v_bitop3_b32 v2, v184, v3, 6 bitop3:0x36
	v_lshlrev_b32_e32 v20, 4, v2
	v_lshlrev_b64 v[2:3], 9, v[0:1]
	v_lshl_add_u64 v[174:175], s[8:9], 0, v[2:3]
	v_mov_b64_e32 v[2:3], s[6:7]
	v_mad_i64_i32 v[176:177], s[6:7], v0, s30, v[2:3]
	v_mov_b32_e32 v0, v161
	v_mov_b32_e32 v1, v161
	v_mov_b32_e32 v2, v161
	v_mov_b32_e32 v3, v161
	v_mov_b32_e32 v4, v161
	v_mov_b32_e32 v5, v161
	v_mov_b32_e32 v6, v161
	v_mov_b32_e32 v7, v161
	v_mov_b32_e32 v8, v161
	v_mov_b32_e32 v9, v161
	v_mov_b32_e32 v10, v161
	v_mov_b32_e32 v12, v161
	v_mov_b32_e32 v13, v161
	v_add_u32_e32 v188, v16, v17
	v_add_u32_e32 v189, v16, v18
	v_add_u32_e32 v190, v16, v19
	v_add_u32_e32 v191, v16, v20
	v_add_u32_e32 v216, v21, v170
	v_mov_b64_e32 v[30:31], v[14:15]
	v_mov_b64_e32 v[46:47], v[14:15]
	v_mov_b64_e32 v[62:63], v[14:15]
	s_mov_b32 s15, 0
	v_mov_b32_e32 v218, 0
	v_mov_b64_e32 v[28:29], v[12:13]
	v_mov_b64_e32 v[26:27], v[10:11]
	v_mov_b64_e32 v[24:25], v[8:9]
	v_mov_b64_e32 v[22:23], v[6:7]
	v_mov_b64_e32 v[20:21], v[4:5]
	v_mov_b64_e32 v[18:19], v[2:3]
	v_mov_b64_e32 v[16:17], v[0:1]
	v_mov_b64_e32 v[44:45], v[12:13]
	v_mov_b64_e32 v[42:43], v[10:11]
	v_mov_b64_e32 v[40:41], v[8:9]
	v_mov_b64_e32 v[38:39], v[6:7]
	v_mov_b64_e32 v[36:37], v[4:5]
	v_mov_b64_e32 v[34:35], v[2:3]
	v_mov_b64_e32 v[32:33], v[0:1]
	v_mov_b64_e32 v[60:61], v[12:13]
	v_mov_b64_e32 v[58:59], v[10:11]
	v_mov_b64_e32 v[56:57], v[8:9]
	v_mov_b64_e32 v[54:55], v[6:7]
	v_mov_b64_e32 v[52:53], v[4:5]
	v_mov_b64_e32 v[50:51], v[2:3]
	v_mov_b64_e32 v[48:49], v[0:1]
	v_mov_b32_e32 v217, 0
	v_readlane_b32 s53, v252, 1
	v_readlane_b32 s54, v252, 2
	v_readlane_b32 s55, v252, 3
	v_readlane_b32 s58, v252, 6
	v_readlane_b32 s59, v252, 7
	s_branch .LBB0_694
